# phase 5 weight-tile queue rewritten by hand: one parametric transposing tile routine, next tile's index claimed and its loads issued before the current tile is processed
# speedup vs baseline: 1.0045x; 1.0045x over previous
.LBB0_506:
	s_waitcnt vmcnt(0) lgkmcnt(0)
	s_barrier
	s_add_u32 s10, s70, 0x15c88000
	s_addc_u32 s11, s71, 0
	v_mov_b32_e32 v37, 0
	v_mov_b32_e32 v251, 1
	v_mov_b32_e32 v32, 0x18000
	v_and_b32_e32 v1, 15, v0
	v_lshlrev_b32_e32 v2, 4, v1
	v_lshrrev_b32_e32 v3, 4, v0
	v_mul_u32_u24_e32 v4, 0x104, v3
	v_add_u32_e32 v20, v4, v2
	v_add_u32_e32 v21, 0x2080, v20
	v_add_u32_e32 v22, 0x2080, v21
	v_add_u32_e32 v23, 0x2080, v22
	v_add_u32_e32 v24, 0x2080, v23
	v_add_u32_e32 v25, 0x2080, v24
	v_add_u32_e32 v26, 0x2080, v25
	v_add_u32_e32 v27, 0x2080, v26
	v_and_b32_e32 v5, 7, v0
	v_lshlrev_b32_e32 v5, 3, v5
	v_lshrrev_b32_e32 v6, 3, v0
	v_mul_u32_u24_e32 v7, 0x104, v5
	v_lshl_add_u32 v7, v6, 2, v7
	v_lshlrev_b32_e32 v28, 2, v3
	v_lshlrev_b32_e32 v31, 1, v5
	s_and_saveexec_b64 s[26:27], s[4:5]
	s_cbranch_execz .Ltq_c28
	global_atomic_add v250, v37, v251, s[10:11] sc0
.Ltq_c28:
	s_mov_b64 exec, s[26:27]
	s_waitcnt vmcnt(0)
	s_and_saveexec_b64 s[26:27], s[4:5]
	ds_write_b32 v32, v250
	s_mov_b64 exec, s[26:27]
	s_waitcnt lgkmcnt(0)
	s_barrier
	ds_read_b32 v33, v32
	s_waitcnt lgkmcnt(0)
	v_readfirstlane_b32 s6, v33
	s_nop 3
	s_cmp_ge_u32 s6, 0x780
	s_cbranch_scc1 .LBB0_571
	s_cmp_lt_u32 s6, 0x580
	s_cbranch_scc0 .Ltq_oth_p
	s_mul_i32 s7, s6, 0x1746
	s_lshr_b32 s7, s7, 20
	s_mul_i32 s8, s7, 0xb0
	s_sub_u32 s8, s6, s8
	s_mul_i32 s9, s7, 0xb00000
	s_lshl_b32 s29, s8, 8
	s_add_u32 s9, s9, s29
	s_add_u32 s12, s52, s9
	s_addc_u32 s13, s53, 0
	s_mov_b32 s14, 0xb000
	s_mov_b32 s15, 0x160000
	s_lshl_b32 s9, s8, 18
	s_lshl_b32 s29, s7, 9
	s_add_u32 s9, s9, s29
	s_add_u32 s9, s9, 0x3a00000
	s_add_u32 s22, s70, s9
	s_addc_u32 s23, s71, 0
	s_mov_b32 s24, 12
	s_lshl_b32 s9, s7, 10
	s_add_u32 s20, s50, s9
	s_addc_u32 s21, s51, 0
	s_mov_b32 s25, 1
	s_branch .Ltq_ld_p
.Ltq_oth_p:
	s_sub_u32 s6, s6, 0x580
	s_cmp_lt_u32 s6, 0x100
	s_cbranch_scc0 .Ltq_out_p
	s_lshr_b32 s30, s6, 7
	s_and_b32 s6, s6, 0x7f
	s_and_b32 s8, s6, 31
	s_lshr_b32 s7, s6, 5
	s_lshl_b32 s9, s7, 21
	s_lshl_b32 s29, s8, 8
	s_add_u32 s9, s9, s29
	s_lshl_b32 s29, s30, 23
	s_add_u32 s9, s9, s29
	s_add_u32 s12, s46, s9
	s_addc_u32 s13, s47, 0
	s_lshl_b32 s9, s8, 17
	s_lshl_b32 s29, s7, 9
	s_add_u32 s9, s9, s29
	s_lshl_b32 s29, s30, 22
	s_add_u32 s9, s9, s29
	s_add_u32 s9, s9, 0x6600000
	s_add_u32 s22, s70, s9
	s_addc_u32 s23, s71, 0
	s_mov_b32 s24, 11
	s_branch .Ltq_ns_p
.Ltq_out_p:
	s_sub_u32 s6, s6, 0x100
	s_and_b32 s8, s6, 31
	s_lshr_b32 s7, s6, 5
	s_lshl_b32 s9, s7, 21
	s_lshl_b32 s29, s8, 8
	s_add_u32 s9, s9, s29
	s_add_u32 s12, s48, s9
	s_addc_u32 s13, s49, 0
	s_lshl_b32 s9, s8, 18
	s_lshl_b32 s29, s7, 9
	s_add_u32 s9, s9, s29
	s_add_u32 s9, s9, 0x6e00000
	s_add_u32 s22, s70, s9
	s_addc_u32 s23, s71, 0
	s_mov_b32 s24, 12
.Ltq_ns_p:
	s_mov_b32 s14, 0x2000
	s_mov_b32 s15, 0x40000
	s_mov_b32 s25, 0
.Ltq_ld_p:
	v_mul_u32_u24_e32 v180, s14, v3
	v_add_u32_e32 v180, v180, v2
	v_add_u32_e32 v181, s15, v180
	v_add_u32_e32 v182, s15, v181
	v_add_u32_e32 v183, s15, v182
	v_add_u32_e32 v184, s15, v183
	v_add_u32_e32 v185, s15, v184
	v_add_u32_e32 v186, s15, v185
	v_add_u32_e32 v187, s15, v186
	global_load_dwordx4 v[40:43], v180, s[12:13]
	global_load_dwordx4 v[44:47], v181, s[12:13]
	global_load_dwordx4 v[48:51], v182, s[12:13]
	global_load_dwordx4 v[52:55], v183, s[12:13]
	global_load_dwordx4 v[56:59], v184, s[12:13]
	global_load_dwordx4 v[60:63], v185, s[12:13]
	global_load_dwordx4 v[64:67], v186, s[12:13]
	global_load_dwordx4 v[68:71], v187, s[12:13]
	s_cmp_eq_u32 s25, 0
	s_cbranch_scc1 .Ltq_one_p
	global_load_dword v72, v28, s[20:21]
	global_load_dword v73, v28, s[20:21] offset:128
	global_load_dword v74, v28, s[20:21] offset:256
	global_load_dword v75, v28, s[20:21] offset:384
	global_load_dword v76, v28, s[20:21] offset:512
	global_load_dword v77, v28, s[20:21] offset:640
	global_load_dword v78, v28, s[20:21] offset:768
	global_load_dword v79, v28, s[20:21] offset:896
	s_branch .Ltq_sd_p
.Ltq_one_p:
	v_mov_b32_e32 v72, 1.0
	v_mov_b32_e32 v73, 1.0
	v_mov_b32_e32 v74, 1.0
	v_mov_b32_e32 v75, 1.0
	v_mov_b32_e32 v76, 1.0
	v_mov_b32_e32 v77, 1.0
	v_mov_b32_e32 v78, 1.0
	v_mov_b32_e32 v79, 1.0
.Ltq_sd_p:
	s_and_saveexec_b64 s[26:27], s[4:5]
	s_cbranch_execz .Ltq_c154
	global_atomic_add v250, v37, v251, s[10:11] sc0
.Ltq_c154:
	s_mov_b64 exec, s[26:27]
	s_waitcnt vmcnt(0)
.Ltq_loop:
	v_mov_b32_e32 v140, v40
	v_mov_b32_e32 v141, v41
	v_mov_b32_e32 v142, v42
	v_mov_b32_e32 v143, v43
	v_mov_b32_e32 v144, v44
	v_mov_b32_e32 v145, v45
	v_mov_b32_e32 v146, v46
	v_mov_b32_e32 v147, v47
	v_mov_b32_e32 v148, v48
	v_mov_b32_e32 v149, v49
	v_mov_b32_e32 v150, v50
	v_mov_b32_e32 v151, v51
	v_mov_b32_e32 v152, v52
	v_mov_b32_e32 v153, v53
	v_mov_b32_e32 v154, v54
	v_mov_b32_e32 v155, v55
	v_mov_b32_e32 v156, v56
	v_mov_b32_e32 v157, v57
	v_mov_b32_e32 v158, v58
	v_mov_b32_e32 v159, v59
	v_mov_b32_e32 v160, v60
	v_mov_b32_e32 v161, v61
	v_mov_b32_e32 v162, v62
	v_mov_b32_e32 v163, v63
	v_mov_b32_e32 v164, v64
	v_mov_b32_e32 v165, v65
	v_mov_b32_e32 v166, v66
	v_mov_b32_e32 v167, v67
	v_mov_b32_e32 v168, v68
	v_mov_b32_e32 v169, v69
	v_mov_b32_e32 v170, v70
	v_mov_b32_e32 v171, v71
	v_mov_b32_e32 v172, v72
	v_mov_b32_e32 v173, v73
	v_mov_b32_e32 v174, v74
	v_mov_b32_e32 v175, v75
	v_mov_b32_e32 v176, v76
	v_mov_b32_e32 v177, v77
	v_mov_b32_e32 v178, v78
	v_mov_b32_e32 v179, v79
	s_mov_b64 s[16:17], s[22:23]
	s_mov_b32 s18, s24
	s_and_saveexec_b64 s[26:27], s[4:5]
	ds_write_b32 v32, v250
	s_mov_b64 exec, s[26:27]
	s_waitcnt lgkmcnt(0)
	s_barrier
	ds_read_b32 v33, v32
	s_waitcnt lgkmcnt(0)
	v_readfirstlane_b32 s6, v33
	s_nop 3
	s_mov_b32 s28, 0
	s_cmp_ge_u32 s6, 0x780
	s_cbranch_scc1 .Ltq_nonext
	s_cmp_lt_u32 s6, 0x580
	s_cbranch_scc0 .Ltq_oth_n
	s_mul_i32 s7, s6, 0x1746
	s_lshr_b32 s7, s7, 20
	s_mul_i32 s8, s7, 0xb0
	s_sub_u32 s8, s6, s8
	s_mul_i32 s9, s7, 0xb00000
	s_lshl_b32 s29, s8, 8
	s_add_u32 s9, s9, s29
	s_add_u32 s12, s52, s9
	s_addc_u32 s13, s53, 0
	s_mov_b32 s14, 0xb000
	s_mov_b32 s15, 0x160000
	s_lshl_b32 s9, s8, 18
	s_lshl_b32 s29, s7, 9
	s_add_u32 s9, s9, s29
	s_add_u32 s9, s9, 0x3a00000
	s_add_u32 s22, s70, s9
	s_addc_u32 s23, s71, 0
	s_mov_b32 s24, 12
	s_lshl_b32 s9, s7, 10
	s_add_u32 s20, s50, s9
	s_addc_u32 s21, s51, 0
	s_mov_b32 s25, 1
	s_branch .Ltq_ld_n

.Ltq_c324:
	s_mov_b64 exec, s[26:27]
	s_mov_b32 s28, 1
.Ltq_nonext:
	v_mul_f32_e32 v140, v140, v172
	v_mul_f32_e32 v141, v141, v172
	v_mul_f32_e32 v142, v142, v172
	v_mul_f32_e32 v143, v143, v172
	v_mul_f32_e32 v144, v144, v173
	v_mul_f32_e32 v145, v145, v173
	v_mul_f32_e32 v146, v146, v173
	v_mul_f32_e32 v147, v147, v173
	v_mul_f32_e32 v148, v148, v174
	v_mul_f32_e32 v149, v149, v174
	v_mul_f32_e32 v150, v150, v174
	v_mul_f32_e32 v151, v151, v174
	v_mul_f32_e32 v152, v152, v175
	v_mul_f32_e32 v153, v153, v175
	v_mul_f32_e32 v154, v154, v175
	v_mul_f32_e32 v155, v155, v175
	v_mul_f32_e32 v156, v156, v176
	v_mul_f32_e32 v157, v157, v176
	v_mul_f32_e32 v158, v158, v176
	v_mul_f32_e32 v159, v159, v176
	v_mul_f32_e32 v160, v160, v177
	v_mul_f32_e32 v161, v161, v177
	v_mul_f32_e32 v162, v162, v177
	v_mul_f32_e32 v163, v163, v177
	v_mul_f32_e32 v164, v164, v178
	v_mul_f32_e32 v165, v165, v178
	v_mul_f32_e32 v166, v166, v178
	v_mul_f32_e32 v167, v167, v178
	v_mul_f32_e32 v168, v168, v179
	v_mul_f32_e32 v169, v169, v179
	v_mul_f32_e32 v170, v170, v179
	v_mul_f32_e32 v171, v171, v179
	ds_write2_b32 v20, v140, v141 offset1:1
	ds_write2_b32 v20, v142, v143 offset0:2 offset1:3
	ds_write2_b32 v21, v144, v145 offset1:1
	ds_write2_b32 v21, v146, v147 offset0:2 offset1:3
	ds_write2_b32 v22, v148, v149 offset1:1
	ds_write2_b32 v22, v150, v151 offset0:2 offset1:3
	ds_write2_b32 v23, v152, v153 offset1:1
	ds_write2_b32 v23, v154, v155 offset0:2 offset1:3
	ds_write2_b32 v24, v156, v157 offset1:1
	ds_write2_b32 v24, v158, v159 offset0:2 offset1:3
	ds_write2_b32 v25, v160, v161 offset1:1
	ds_write2_b32 v25, v162, v163 offset0:2 offset1:3
	ds_write2_b32 v26, v164, v165 offset1:1
	ds_write2_b32 v26, v166, v167 offset0:2 offset1:3
	ds_write2_b32 v27, v168, v169 offset1:1
	ds_write2_b32 v27, v170, v171 offset0:2 offset1:3
	s_waitcnt lgkmcnt(0)
	s_barrier
	v_lshlrev_b32_e32 v29, s18, v6
	v_add_u32_e32 v29, v29, v31
	ds_read_b32 v8, v7 offset:0
	ds_read_b32 v9, v7 offset:260
	ds_read_b32 v10, v7 offset:520
	ds_read_b32 v11, v7 offset:780
	ds_read_b32 v12, v7 offset:1040
	ds_read_b32 v13, v7 offset:1300
	ds_read_b32 v14, v7 offset:1560
	ds_read_b32 v15, v7 offset:1820
	s_waitcnt lgkmcnt(0)
	v_cvt_pk_bf16_f32 v16, v8, v9
	v_cvt_pk_bf16_f32 v17, v10, v11
	v_cvt_pk_bf16_f32 v18, v12, v13
	v_cvt_pk_bf16_f32 v19, v14, v15
	global_store_dwordx4 v29, v[16:19], s[16:17]
	ds_read_b32 v8, v7 offset:16640
	ds_read_b32 v9, v7 offset:16900
	ds_read_b32 v10, v7 offset:17160
	ds_read_b32 v11, v7 offset:17420
	ds_read_b32 v12, v7 offset:17680
	ds_read_b32 v13, v7 offset:17940
	ds_read_b32 v14, v7 offset:18200
	ds_read_b32 v15, v7 offset:18460
	s_waitcnt lgkmcnt(0)
	v_cvt_pk_bf16_f32 v100, v8, v9
	v_cvt_pk_bf16_f32 v101, v10, v11
	v_cvt_pk_bf16_f32 v102, v12, v13
	v_cvt_pk_bf16_f32 v103, v14, v15
	global_store_dwordx4 v29, v[100:103], s[16:17] offset:128
	ds_read_b32 v8, v7 offset:33280
	ds_read_b32 v9, v7 offset:33540
	ds_read_b32 v10, v7 offset:33800
	ds_read_b32 v11, v7 offset:34060
	ds_read_b32 v12, v7 offset:34320
	ds_read_b32 v13, v7 offset:34580
	ds_read_b32 v14, v7 offset:34840
	ds_read_b32 v15, v7 offset:35100
	s_waitcnt lgkmcnt(0)
	v_cvt_pk_bf16_f32 v104, v8, v9
	v_cvt_pk_bf16_f32 v105, v10, v11
	v_cvt_pk_bf16_f32 v106, v12, v13
	v_cvt_pk_bf16_f32 v107, v14, v15
	global_store_dwordx4 v29, v[104:107], s[16:17] offset:256
	ds_read_b32 v8, v7 offset:49920
	ds_read_b32 v9, v7 offset:50180
	ds_read_b32 v10, v7 offset:50440
	ds_read_b32 v11, v7 offset:50700
	ds_read_b32 v12, v7 offset:50960
	ds_read_b32 v13, v7 offset:51220
	ds_read_b32 v14, v7 offset:51480
	ds_read_b32 v15, v7 offset:51740
	s_waitcnt lgkmcnt(0)
	v_cvt_pk_bf16_f32 v108, v8, v9
	v_cvt_pk_bf16_f32 v109, v10, v11
	v_cvt_pk_bf16_f32 v110, v12, v13
	v_cvt_pk_bf16_f32 v111, v14, v15
	global_store_dwordx4 v29, v[108:111], s[16:17] offset:384
	s_barrier
	s_cmp_eq_u32 s28, 0
	s_cbranch_scc1 .LBB0_571
	s_waitcnt vmcnt(4)
	s_branch .Ltq_loop
